# v65 + grid barrier: non-leader workgroups poll the cross-XCD release word directly (one polling hop less per barrier)
# baseline (speedup 1.0000x reference)
.LBB0_129:
	s_or_b64 exec, exec, s[6:7]
	v_cvt_f32_u32_e32 v4, v2
	s_waitcnt vmcnt(0)
	v_readfirstlane_b32 s4, v3
	v_sub_u32_e32 v3, 0, v2
	v_rcp_iflag_f32_e32 v4, v4
	v_add_u32_e32 v5, s4, v1
	v_mul_f32_e32 v4, 0x4f7ffffe, v4
	v_cvt_u32_f32_e32 v4, v4
	v_mul_lo_u32 v1, v3, v4
	v_mul_hi_u32 v1, v4, v1
	v_add_u32_e32 v1, v4, v1
	v_mul_hi_u32 v1, v5, v1
	v_mul_lo_u32 v3, v1, v2
	v_sub_u32_e32 v3, v5, v3
	v_add_u32_e32 v4, 1, v1
	v_cmp_ge_u32_e32 vcc, v3, v2
	s_nop 1
	v_cndmask_b32_e32 v1, v1, v4, vcc
	v_sub_u32_e32 v4, v3, v2
	v_cndmask_b32_e32 v3, v3, v4, vcc
	v_add_u32_e32 v4, 1, v1
	v_cmp_ge_u32_e32 vcc, v3, v2
	v_add_u32_e32 v3, 1, v5
	s_nop 0
	v_cndmask_b32_e32 v1, v1, v4, vcc
	v_mul_lo_u32 v4, v2, v1
	v_add_u32_e32 v2, v4, v2
	v_cmp_ne_u32_e32 vcc, v3, v2
	s_and_saveexec_b64 s[4:5], vcc
	s_xor_b64 s[4:5], exec, s[4:5]
	s_cbranch_execz .LBB0_143
	s_waitcnt lgkmcnt(0)
	s_add_u32 s10, s64, 0x83500
	s_addc_u32 s11, s65, 0
	v_mov_b32_e32 v0, 0
	global_load_dword v0, v0, s[10:11] sc1
	s_waitcnt vmcnt(0)
	v_cmp_eq_u32_e32 vcc, v0, v1
	s_and_saveexec_b64 s[6:7], vcc
	s_cbranch_execz .LBB0_142
	s_add_u32 s8, s64, 0x80200
	s_addc_u32 s9, s65, 0
	s_mov_b32 s22, 1
	s_mov_b64 s[12:13], 0
	v_mov_b32_e32 v0, 0
	s_branch .LBB0_133

.LBB0_513:
	s_or_b64 exec, exec, s[6:7]
	v_cvt_f32_u32_e32 v4, v2
	s_waitcnt vmcnt(0)
	v_readfirstlane_b32 s4, v3
	v_sub_u32_e32 v3, 0, v2
	v_rcp_iflag_f32_e32 v4, v4
	v_add_u32_e32 v5, s4, v1
	v_mul_f32_e32 v4, 0x4f7ffffe, v4
	v_cvt_u32_f32_e32 v4, v4
	v_mul_lo_u32 v1, v3, v4
	v_mul_hi_u32 v1, v4, v1
	v_add_u32_e32 v1, v4, v1
	v_mul_hi_u32 v1, v5, v1
	v_mul_lo_u32 v3, v1, v2
	v_sub_u32_e32 v3, v5, v3
	v_add_u32_e32 v4, 1, v1
	v_cmp_ge_u32_e32 vcc, v3, v2
	s_nop 1
	v_cndmask_b32_e32 v1, v1, v4, vcc
	v_sub_u32_e32 v4, v3, v2
	v_cndmask_b32_e32 v3, v3, v4, vcc
	v_add_u32_e32 v4, 1, v1
	v_cmp_ge_u32_e32 vcc, v3, v2
	v_add_u32_e32 v3, 1, v5
	s_nop 0
	v_cndmask_b32_e32 v1, v1, v4, vcc
	v_mul_lo_u32 v4, v2, v1
	v_add_u32_e32 v2, v4, v2
	v_cmp_ne_u32_e32 vcc, v3, v2
	s_and_saveexec_b64 s[4:5], vcc
	s_xor_b64 s[4:5], exec, s[4:5]
	s_cbranch_execz .LBB0_527
	s_waitcnt lgkmcnt(0)
	s_add_u32 s10, s74, 0x83500
	s_addc_u32 s11, s75, 0
	v_mov_b32_e32 v0, 0
	global_load_dword v0, v0, s[10:11] sc1
	s_waitcnt vmcnt(0)
	v_cmp_eq_u32_e32 vcc, v0, v1
	s_and_saveexec_b64 s[6:7], vcc
	s_cbranch_execz .LBB0_526
	s_add_u32 s8, s74, 0x80200
	s_addc_u32 s9, s75, 0
	s_mov_b32 s22, 1
	s_mov_b64 s[12:13], 0
	v_mov_b32_e32 v0, 0
	s_branch .LBB0_517

.LBB0_585:
	s_or_b64 exec, exec, s[8:9]
	v_cvt_f32_u32_e32 v4, v2
	s_waitcnt vmcnt(0)
	v_readfirstlane_b32 s6, v3
	v_sub_u32_e32 v3, 0, v2
	v_rcp_iflag_f32_e32 v4, v4
	v_add_u32_e32 v5, s6, v1
	v_mul_f32_e32 v4, 0x4f7ffffe, v4
	v_cvt_u32_f32_e32 v4, v4
	v_mul_lo_u32 v1, v3, v4
	v_mul_hi_u32 v1, v4, v1
	v_add_u32_e32 v1, v4, v1
	v_mul_hi_u32 v1, v5, v1
	v_mul_lo_u32 v3, v1, v2
	v_sub_u32_e32 v3, v5, v3
	v_add_u32_e32 v4, 1, v1
	v_cmp_ge_u32_e32 vcc, v3, v2
	s_nop 1
	v_cndmask_b32_e32 v1, v1, v4, vcc
	v_sub_u32_e32 v4, v3, v2
	v_cndmask_b32_e32 v3, v3, v4, vcc
	v_add_u32_e32 v4, 1, v1
	v_cmp_ge_u32_e32 vcc, v3, v2
	v_add_u32_e32 v3, 1, v5
	s_nop 0
	v_cndmask_b32_e32 v1, v1, v4, vcc
	v_mul_lo_u32 v4, v2, v1
	v_add_u32_e32 v2, v4, v2
	v_cmp_ne_u32_e32 vcc, v3, v2
	s_and_saveexec_b64 s[6:7], vcc
	s_xor_b64 s[6:7], exec, s[6:7]
	s_cbranch_execz .LBB0_599
	s_waitcnt lgkmcnt(0)
	s_add_u32 s12, s74, 0x83500
	s_addc_u32 s13, s75, 0
	v_mov_b32_e32 v0, 0
	global_load_dword v0, v0, s[12:13] sc1
	s_waitcnt vmcnt(0)
	v_cmp_eq_u32_e32 vcc, v0, v1
	s_and_saveexec_b64 s[8:9], vcc
	s_cbranch_execz .LBB0_598
	s_add_u32 s10, s74, 0x80200
	s_addc_u32 s11, s75, 0
	s_mov_b32 s24, 1
	s_mov_b64 s[14:15], 0
	v_mov_b32_e32 v0, 0
	s_branch .LBB0_589

.LBB0_672:
	s_or_b64 exec, exec, s[14:15]
	v_cvt_f32_u32_e32 v4, v2
	s_waitcnt vmcnt(0)
	v_readfirstlane_b32 s12, v3
	v_sub_u32_e32 v3, 0, v2
	v_rcp_iflag_f32_e32 v4, v4
	v_add_u32_e32 v5, s12, v1
	v_mul_f32_e32 v4, 0x4f7ffffe, v4
	v_cvt_u32_f32_e32 v4, v4
	v_mul_lo_u32 v1, v3, v4
	v_mul_hi_u32 v1, v4, v1
	v_add_u32_e32 v1, v4, v1
	v_mul_hi_u32 v1, v5, v1
	v_mul_lo_u32 v3, v1, v2
	v_sub_u32_e32 v3, v5, v3
	v_add_u32_e32 v4, 1, v1
	v_cmp_ge_u32_e32 vcc, v3, v2
	s_nop 1
	v_cndmask_b32_e32 v1, v1, v4, vcc
	v_sub_u32_e32 v4, v3, v2
	v_cndmask_b32_e32 v3, v3, v4, vcc
	v_add_u32_e32 v4, 1, v1
	v_cmp_ge_u32_e32 vcc, v3, v2
	v_add_u32_e32 v3, 1, v5
	s_nop 0
	v_cndmask_b32_e32 v1, v1, v4, vcc
	v_mul_lo_u32 v4, v2, v1
	v_add_u32_e32 v2, v4, v2
	v_cmp_ne_u32_e32 vcc, v3, v2
	s_and_saveexec_b64 s[12:13], vcc
	s_xor_b64 s[12:13], exec, s[12:13]
	s_cbranch_execz .LBB0_686
	s_waitcnt lgkmcnt(0)
	s_add_u32 s18, s74, 0x83500
	s_addc_u32 s19, s75, 0
	v_mov_b32_e32 v0, 0
	global_load_dword v0, v0, s[18:19] sc1
	s_waitcnt vmcnt(0)
	v_cmp_eq_u32_e32 vcc, v0, v1
	s_and_saveexec_b64 s[14:15], vcc
	s_cbranch_execz .LBB0_685
	s_add_u32 s16, s74, 0x80200
	s_addc_u32 s17, s75, 0
	s_mov_b32 s30, 1
	s_mov_b64 s[20:21], 0
	v_mov_b32_e32 v0, 0
	s_branch .LBB0_676

.LBB0_862:
	s_or_b64 exec, exec, s[8:9]
	v_cvt_f32_u32_e32 v4, v2
	s_waitcnt vmcnt(0)
	v_readfirstlane_b32 s6, v3
	v_sub_u32_e32 v3, 0, v2
	v_rcp_iflag_f32_e32 v4, v4
	v_add_u32_e32 v5, s6, v1
	v_mul_f32_e32 v4, 0x4f7ffffe, v4
	v_cvt_u32_f32_e32 v4, v4
	v_mul_lo_u32 v1, v3, v4
	v_mul_hi_u32 v1, v4, v1
	v_add_u32_e32 v1, v4, v1
	v_mul_hi_u32 v1, v5, v1
	v_mul_lo_u32 v3, v1, v2
	v_sub_u32_e32 v3, v5, v3
	v_add_u32_e32 v4, 1, v1
	v_cmp_ge_u32_e32 vcc, v3, v2
	s_nop 1
	v_cndmask_b32_e32 v1, v1, v4, vcc
	v_sub_u32_e32 v4, v3, v2
	v_cndmask_b32_e32 v3, v3, v4, vcc
	v_add_u32_e32 v4, 1, v1
	v_cmp_ge_u32_e32 vcc, v3, v2
	v_add_u32_e32 v3, 1, v5
	s_nop 0
	v_cndmask_b32_e32 v1, v1, v4, vcc
	v_mul_lo_u32 v4, v2, v1
	v_add_u32_e32 v2, v4, v2
	v_cmp_ne_u32_e32 vcc, v3, v2
	s_and_saveexec_b64 s[6:7], vcc
	s_xor_b64 s[6:7], exec, s[6:7]
	s_cbranch_execz .LBB0_876
	s_waitcnt lgkmcnt(0)
	s_add_u32 s16, s74, 0x83500
	s_addc_u32 s17, s75, 0
	v_mov_b32_e32 v0, 0
	global_load_dword v0, v0, s[16:17] sc1
	s_waitcnt vmcnt(0)
	v_cmp_eq_u32_e32 vcc, v0, v1
	s_and_saveexec_b64 s[8:9], vcc
	s_cbranch_execz .LBB0_875
	s_add_u32 s10, s74, 0x80200
	s_addc_u32 s11, s75, 0
	s_mov_b32 s28, 1
	s_mov_b64 s[18:19], 0
	v_mov_b32_e32 v0, 0
	s_branch .LBB0_866

.LBB0_970:
	s_or_b64 exec, exec, s[8:9]
	v_cvt_f32_u32_e32 v4, v2
	s_waitcnt vmcnt(0)
	v_readfirstlane_b32 s6, v3
	v_sub_u32_e32 v3, 0, v2
	v_rcp_iflag_f32_e32 v4, v4
	v_add_u32_e32 v5, s6, v1
	v_mul_f32_e32 v4, 0x4f7ffffe, v4
	v_cvt_u32_f32_e32 v4, v4
	v_mul_lo_u32 v1, v3, v4
	v_mul_hi_u32 v1, v4, v1
	v_add_u32_e32 v1, v4, v1
	v_mul_hi_u32 v1, v5, v1
	v_mul_lo_u32 v3, v1, v2
	v_sub_u32_e32 v3, v5, v3
	v_add_u32_e32 v4, 1, v1
	v_cmp_ge_u32_e32 vcc, v3, v2
	s_nop 1
	v_cndmask_b32_e32 v1, v1, v4, vcc
	v_sub_u32_e32 v4, v3, v2
	v_cndmask_b32_e32 v3, v3, v4, vcc
	v_add_u32_e32 v4, 1, v1
	v_cmp_ge_u32_e32 vcc, v3, v2
	v_add_u32_e32 v3, 1, v5
	s_nop 0
	v_cndmask_b32_e32 v1, v1, v4, vcc
	v_mul_lo_u32 v4, v2, v1
	v_add_u32_e32 v2, v4, v2
	v_cmp_ne_u32_e32 vcc, v3, v2
	s_and_saveexec_b64 s[6:7], vcc
	s_xor_b64 s[6:7], exec, s[6:7]
	s_cbranch_execz .LBB0_984
	s_waitcnt lgkmcnt(0)
	s_add_u32 s16, s74, 0x83500
	s_addc_u32 s17, s75, 0
	v_mov_b32_e32 v0, 0
	global_load_dword v0, v0, s[16:17] sc1
	s_waitcnt vmcnt(0)
	v_cmp_eq_u32_e32 vcc, v0, v1
	s_and_saveexec_b64 s[8:9], vcc
	s_cbranch_execz .LBB0_983
	s_add_u32 s10, s74, 0x80200
	s_addc_u32 s11, s75, 0
	s_mov_b32 s30, 1
	s_mov_b64 s[20:21], 0
	v_mov_b32_e32 v0, 0
	s_branch .LBB0_974

.LBB0_1037:
	s_or_b64 exec, exec, s[8:9]
	v_cvt_f32_u32_e32 v4, v2
	s_waitcnt vmcnt(0)
	v_readfirstlane_b32 s6, v3
	v_sub_u32_e32 v3, 0, v2
	v_rcp_iflag_f32_e32 v4, v4
	v_add_u32_e32 v5, s6, v1
	v_mul_f32_e32 v4, 0x4f7ffffe, v4
	v_cvt_u32_f32_e32 v4, v4
	v_mul_lo_u32 v1, v3, v4
	v_mul_hi_u32 v1, v4, v1
	v_add_u32_e32 v1, v4, v1
	v_mul_hi_u32 v1, v5, v1
	v_mul_lo_u32 v3, v1, v2
	v_sub_u32_e32 v3, v5, v3
	v_add_u32_e32 v4, 1, v1
	v_cmp_ge_u32_e32 vcc, v3, v2
	s_nop 1
	v_cndmask_b32_e32 v1, v1, v4, vcc
	v_sub_u32_e32 v4, v3, v2
	v_cndmask_b32_e32 v3, v3, v4, vcc
	v_add_u32_e32 v4, 1, v1
	v_cmp_ge_u32_e32 vcc, v3, v2
	v_add_u32_e32 v3, 1, v5
	s_nop 0
	v_cndmask_b32_e32 v1, v1, v4, vcc
	v_mul_lo_u32 v4, v2, v1
	v_add_u32_e32 v2, v4, v2
	v_cmp_ne_u32_e32 vcc, v3, v2
	s_and_saveexec_b64 s[6:7], vcc
	s_xor_b64 s[6:7], exec, s[6:7]
	s_cbranch_execz .LBB0_1051
	s_waitcnt lgkmcnt(0)
	s_add_u32 s18, s74, 0x83500
	s_addc_u32 s19, s75, 0
	v_mov_b32_e32 v0, 0
	global_load_dword v0, v0, s[18:19] sc1
	s_waitcnt vmcnt(0)
	v_cmp_eq_u32_e32 vcc, v0, v1
	s_and_saveexec_b64 s[8:9], vcc
	s_cbranch_execz .LBB0_1050
	s_add_u32 s10, s74, 0x80200
	s_addc_u32 s11, s75, 0
	s_mov_b32 s30, 1
	s_mov_b64 s[20:21], 0
	v_mov_b32_e32 v0, 0
	s_branch .LBB0_1041

.LBB0_1215:
	s_or_b64 exec, exec, s[6:7]
	v_cvt_f32_u32_e32 v4, v2
	s_waitcnt vmcnt(0)
	v_readfirstlane_b32 s4, v3
	v_sub_u32_e32 v3, 0, v2
	v_rcp_iflag_f32_e32 v4, v4
	v_add_u32_e32 v5, s4, v1
	v_mul_f32_e32 v4, 0x4f7ffffe, v4
	v_cvt_u32_f32_e32 v4, v4
	v_mul_lo_u32 v1, v3, v4
	v_mul_hi_u32 v1, v4, v1
	v_add_u32_e32 v1, v4, v1
	v_mul_hi_u32 v1, v5, v1
	v_mul_lo_u32 v3, v1, v2
	v_sub_u32_e32 v3, v5, v3
	v_add_u32_e32 v4, 1, v1
	v_cmp_ge_u32_e32 vcc, v3, v2
	s_nop 1
	v_cndmask_b32_e32 v1, v1, v4, vcc
	v_sub_u32_e32 v4, v3, v2
	v_cndmask_b32_e32 v3, v3, v4, vcc
	v_add_u32_e32 v4, 1, v1
	v_cmp_ge_u32_e32 vcc, v3, v2
	v_add_u32_e32 v3, 1, v5
	s_nop 0
	v_cndmask_b32_e32 v1, v1, v4, vcc
	v_mul_lo_u32 v4, v2, v1
	v_add_u32_e32 v2, v4, v2
	v_cmp_ne_u32_e32 vcc, v3, v2
	s_and_saveexec_b64 s[4:5], vcc
	s_xor_b64 s[4:5], exec, s[4:5]
	s_cbranch_execz .LBB0_1229
	s_waitcnt lgkmcnt(0)
	s_add_u32 s10, s74, 0x83500
	s_addc_u32 s11, s75, 0
	v_mov_b32_e32 v0, 0
	global_load_dword v0, v0, s[10:11] sc1
	s_waitcnt vmcnt(0)
	v_cmp_eq_u32_e32 vcc, v0, v1
	s_and_saveexec_b64 s[6:7], vcc
	s_cbranch_execz .LBB0_1228
	s_add_u32 s8, s74, 0x80200
	s_addc_u32 s9, s75, 0
	s_mov_b32 s26, 1
	s_mov_b64 s[16:17], 0
	v_mov_b32_e32 v0, 0
	s_branch .LBB0_1219
